# C tile loop hot-path layout too: diagonal-mask, masked-tile and rescale blocks of both halves out of line
# speedup vs baseline: 1.0035x; 1.0035x over previous
; #define SBAR() __builtin_amdgcn_sched_barrier(0)
; #define PIN(x) asm volatile("" : "+v"(x))
; #define MF(a_, b_, c_) __builtin_amdgcn_mfma_f32_32x32x16_bf16(a_, b_, c_, 0, 0, 0)
; #define PVM(j_) o[(j_) % NDB] = MF(vq[(j_) & 3], pw[(j_) / NDB], o[(j_) % NDB])
; template <int KIND> DI void attn_unit(const Params& P, int b, int h, int qb, char* shm, float lam, bool dry = false) {
;     ...
;         ATT_KLD(sn, 0); ATT_XLD(sn);
;         SBAR();
;     ...
;         G1(pb0 = MF(kf[0], qr[0], negm), 0, w0, 0);  G1(pb1 = MF(kf[1], qr[0], negm), 2, w0, 1);
;         G1(pb0 = MF(kf[2], qr[1], pb0), 4, w0, 2);   G1(pb1 = MF(kf[3], qr[1], pb1), 6, w0, 3);
;         ATT_KLD(sn, 1);
;         SBAR();
;         G1(pb0 = MF(kf[0], qr[2], pb0), 8, w1, 0);   G1(pb1 = MF(kf[1], qr[2], pb1), 10, w1, 1);
;         LDV(0); SBAR();
;         G1(pb0 = MF(kf[2], qr[3], pb0), 12, w1, 2);
;         LDV(1); SBAR();
;         G1(pb1 = MF(kf[3], qr[3], pb1), 14, w1, 3);
;         LDV(2); SBAR();
;     ...
;         if (KIND == 2) { pb0 = MF(x0, ones, pb0); pb1 = MF(x1, ones, pb1); }
;         pw[0] = __builtin_bit_cast(bf16x8, w0); pw[1] = __builtin_bit_cast(bf16x8, w1);
;     ...
;         if (NDB == 4) {
;             LDV(3); PVM(0); E4(0, w0, 0); PIN(pa1); PIN(sacc); PIN(w0); SBAR();
;             LDV(4); PVM(1); E4(2, w0, 1); PIN(pa1); PIN(sacc); PIN(w0); SBAR();
;             LDV(5); PVM(2); E4(4, w0, 2); PIN(pa1); PIN(sacc); PIN(w0); SBAR();
;             LDV(6); PVM(3); E4(6, w0, 3); PIN(pa1); PIN(sacc); PIN(w0); SBAR();
;             LDV(7); PVM(4); E4(8, w1, 0); PIN(pa1); PIN(sacc); PIN(w1); SBAR();
;             LDV(8); PVM(5); E4(10, w1, 1); PIN(pa1); PIN(sacc); PIN(w1); SBAR();
;             LDV(9); PVM(6); E4(12, w1, 2); PIN(pa1); PIN(sacc); PIN(w1); SBAR();
;             LDV(10); PVM(7); E4(14, w1, 3); PIN(pa1); PIN(sacc); PIN(w1); SBAR();
;         } else {
;             LDV(3); PVM(0); E4(0, w0, 0); E4(2, w0, 1); PIN(pa1); PIN(sacc); PIN(w0); SBAR();
;             LDV(4); PVM(1); E4(4, w0, 2); E4(6, w0, 3); PIN(pa1); PIN(sacc); PIN(w0); SBAR();
;             LDV(5); PVM(2); E4(8, w1, 0); E4(10, w1, 1); PIN(pa1); PIN(sacc); PIN(w1); SBAR();
;             LDV(6); PVM(3); E4(12, w1, 2); E4(14, w1, 3); PIN(pa1); PIN(sacc); PIN(w1); SBAR();
;         }
;     ...
;         pw[2] = __builtin_bit_cast(bf16x8, w0); pw[3] = __builtin_bit_cast(bf16x8, w1);
;         lsum += sacc;
;         ATT_FIX(pb0, pb1, ATT_TILE(i + 1));
.LBB0_355:
	s_add_i32 s18, s34, 0x8400
	s_cmp_lg_u32 s34, 0x18c00
	s_cselect_b32 s29, s18, 0
	s_add_i32 s18, s29, 0
	v_add_u32_e32 v84, s18, v168
	v_add_u32_e32 v186, v84, v167
	ds_read_b128 v[100:103], v186
	ds_read_b128 v[174:177], v186 offset:512
	ds_read_b128 v[178:181], v186 offset:2048
	ds_read_b128 v[182:185], v186 offset:2560
	ds_read_b128 v[190:193], v84 offset:32768
	ds_read_b128 v[196:199], v84 offset:33280
	v_exp_f32_e32 v116, v116
	v_exp_f32_e32 v117, v117
	s_nop 0
	v_cvt_pk_bf16_f32 v152, v116, v117
	v_add_f32_e32 v84, 0, v116
	v_add_f32_e32 v84, v117, v84
	v_exp_f32_e32 v118, v118
	v_exp_f32_e32 v119, v119
	v_add_f32_e32 v84, v84, v118
	v_add_f32_e32 v84, v119, v84
	v_cvt_pk_bf16_f32 v153, v118, v119
	v_exp_f32_e32 v120, v120
	v_exp_f32_e32 v121, v121
	v_add_f32_e32 v84, v84, v120
	v_add_f32_e32 v187, v121, v84
	v_cvt_pk_bf16_f32 v154, v120, v121
	s_waitcnt lgkmcnt(5)
	v_mfma_f32_32x32x16_bf16 v[84:99], v[100:103], v[144:147], v[20:35]
	v_exp_f32_e32 v122, v122
	v_exp_f32_e32 v123, v123
	s_waitcnt lgkmcnt(4)
	v_mfma_f32_32x32x16_bf16 v[100:115], v[174:177], v[144:147], v[20:35]
	s_add_i32 s18, s34, 0
	v_exp_f32_e32 v124, v124
	v_exp_f32_e32 v125, v125
	s_waitcnt lgkmcnt(3)
	v_mfma_f32_32x32x16_bf16 v[84:99], v[178:181], v[140:143], v[84:99]
	v_add3_u32 v68, s18, v170, v171
	v_add_f32_e32 v72, v187, v122
	v_cvt_pk_bf16_f32 v148, v124, v125
	v_add_u32_e32 v164, v68, v172
	s_waitcnt lgkmcnt(0)
	v_add_f32_e32 v187, v123, v72
	v_cvt_pk_bf16_f32 v155, v122, v123
	v_mfma_f32_32x32x16_bf16 v[100:115], v[182:185], v[140:143], v[100:115]
	ds_read_b128 v[72:75], v186 offset:4096
	ds_read_b128 v[80:83], v186 offset:4608
	ds_read_b128 v[174:177], v186 offset:6144
	ds_read_b128 v[178:181], v186 offset:6656
	s_waitcnt lgkmcnt(3)
	v_mfma_f32_32x32x16_bf16 v[84:99], v[72:75], v[136:139], v[84:99]
	v_add_f32_e32 v72, v187, v124
	v_add_f32_e32 v72, v125, v72
	s_waitcnt lgkmcnt(2)
	v_mfma_f32_32x32x16_bf16 v[100:115], v[80:83], v[136:139], v[100:115]
	v_exp_f32_e32 v126, v126
	v_exp_f32_e32 v127, v127
	v_add_f32_e32 v72, v72, v126
	v_add_f32_e32 v80, v127, v72
	v_cvt_pk_bf16_f32 v149, v126, v127
	ds_read_b64_tr_b16 v[72:73], v164 offset:16384
	ds_read_b64_tr_b16 v[74:75], v164 offset:16896
	s_waitcnt lgkmcnt(3)
	v_mfma_f32_32x32x16_bf16 v[84:99], v[174:177], v[132:135], v[84:99]
	v_exp_f32_e32 v128, v128
	v_exp_f32_e32 v129, v129
	v_add_f32_e32 v80, v80, v128
	v_add_f32_e32 v174, v129, v80
	v_cvt_pk_bf16_f32 v150, v128, v129
	ds_read_b64_tr_b16 v[80:81], v164 offset:20480
	ds_read_b64_tr_b16 v[82:83], v164 offset:20992
	s_waitcnt lgkmcnt(4)
	v_mfma_f32_32x32x16_bf16 v[100:115], v[178:181], v[132:135], v[100:115]
	v_exp_f32_e32 v130, v130
	v_exp_f32_e32 v131, v131
	v_add_f32_e32 v151, v174, v130
	v_add_f32_e32 v174, v131, v151
	v_cvt_pk_bf16_f32 v151, v130, v131
	ds_read_b64_tr_b16 v[124:125], v164 offset:17408
	ds_read_b64_tr_b16 v[126:127], v164 offset:17920
	v_mfma_f32_32x32x16_bf16 v[84:99], v[190:193], v[0:3], v[84:99]
	v_exp_f32_e32 v4, v4
	v_exp_f32_e32 v5, v5
	v_exp_f32_e32 v6, v6
	v_exp_f32_e32 v7, v7
	v_cvt_pk_bf16_f32 v190, v4, v5
	v_mfma_f32_32x32x16_bf16 v[100:115], v[196:199], v[0:3], v[100:115]
	ds_read_b64_tr_b16 v[68:69], v164 offset:21504
	ds_read_b64_tr_b16 v[70:71], v164 offset:22016
	s_waitcnt lgkmcnt(6)
	v_mfma_f32_32x32x16_bf16 v[52:67], v[72:75], v[152:155], v[52:67]
	v_add_f32_e32 v72, v4, v174
	v_add_f32_e32 v76, v5, v72
	v_add_f32_e32 v73, v6, v76
	v_add_f32_e32 v76, v7, v73
	v_cvt_pk_bf16_f32 v191, v6, v7
	v_exp_f32_e32 v8, v8
	v_exp_f32_e32 v9, v9
	s_waitcnt lgkmcnt(4)
	v_mfma_f32_32x32x16_bf16 v[36:51], v[80:83], v[152:155], v[36:51]
	v_exp_f32_e32 v10, v10
	v_exp_f32_e32 v11, v11
	v_add_f32_e32 v74, v76, v8
	ds_read_b64_tr_b16 v[116:117], v164 offset:18432
	ds_read_b64_tr_b16 v[118:119], v164 offset:18944
	v_add_f32_e32 v75, v9, v74
	v_add_f32_e32 v75, v10, v75
	v_cvt_pk_bf16_f32 v192, v8, v9
	v_add_f32_e32 v76, v11, v75
	v_cvt_pk_bf16_f32 v193, v10, v11
	v_exp_f32_e32 v12, v12
	s_waitcnt lgkmcnt(4)
	v_mfma_f32_32x32x16_bf16 v[52:67], v[124:127], v[148:151], v[52:67]
	v_exp_f32_e32 v13, v13
	v_exp_f32_e32 v14, v14
	ds_read_b64_tr_b16 v[120:121], v164 offset:22528
	ds_read_b64_tr_b16 v[122:123], v164 offset:23040
	v_exp_f32_e32 v15, v15
	v_add_f32_e32 v72, v76, v12
	v_add_f32_e32 v76, v13, v72
	v_cvt_pk_bf16_f32 v152, v12, v13
	v_add_f32_e32 v73, v14, v76
	v_add_f32_e32 v76, v15, v73
	v_cvt_pk_bf16_f32 v153, v14, v15
	s_waitcnt lgkmcnt(4)
	v_mfma_f32_32x32x16_bf16 v[36:51], v[68:71], v[148:151], v[36:51]
	v_exp_f32_e32 v16, v16
	v_exp_f32_e32 v17, v17
	v_exp_f32_e32 v18, v18
	v_exp_f32_e32 v19, v19
	ds_read_b64_tr_b16 v[124:125], v164 offset:19456
	ds_read_b64_tr_b16 v[126:127], v164 offset:19968
	v_add_f32_e32 v68, v76, v16
	v_add_f32_e32 v68, v17, v68
	v_cvt_pk_bf16_f32 v154, v16, v17
	v_cvt_pk_bf16_f32 v155, v18, v19
	v_add_f32_e32 v68, v18, v68
	v_add_f32_e32 v68, v19, v68
	s_cmp_lg_u32 s22, s35
	s_cbranch_scc0 .Lhotc1_diag
.LBB0_357:
	s_add_i32 s19, s20, 2
	s_cmp_lt_i32 s19, 0
	s_cselect_b64 s[38:39], -1, 0
	s_cmp_gt_i32 s19, s36
	s_waitcnt lgkmcnt(4)
	v_mfma_f32_32x32x16_bf16 v[52:67], v[116:119], v[190:193], v[52:67]
	s_cselect_b64 vcc, -1, 0
	s_or_b64 vcc, s[38:39], vcc
	s_cbranch_vccnz .Lhotc1_mask

; #define ATT_DECIDE(P0, P1, rm_) do { if (__any((rm_) > 6.0f)) { const float dl = fmaxf((rm_), 0.f); mhat += dl; const float f = EX(-dl); lsum *= f; \
;             _Pragma("unroll") for (int r = 0; r < 16; ++r) { P0[r] -= dl; P1[r] -= dl; negm[r] -= dl; } \
;             _Pragma("unroll") for (int i2 = 0; i2 < NDB; ++i2) _Pragma("unroll") for (int r = 0; r < 16; ++r) o[i2][r] *= f; } } while (0)
; template <int KIND> DI void attn_unit(const Params& P, int b, int h, int qb, char* shm, float lam, bool dry = false) {
;     ...
;         if (i + 1 < nt_eff) ATT_DECIDE(pb0, pb1, rm);
.LBB0_359:
	v_cmp_ge_i32_e64 s[18:19], s31, v173
	s_and_b64 vcc, exec, s[18:19]
	s_cbranch_vccnz .LBB0_362


; #define LAS __attribute__((address_space(3)))
; DI float max3f(float a, float b, float c) { float r; asm("v_max3_f32 %0, %1, %2, %3" : "=v"(r) : "v"(a), "v"(b), "v"(c)); return r; }
; DI float swapmax(float m) { auto rr = __builtin_amdgcn_permlane32_swap(__float_as_uint(m), __float_as_uint(m), false, false); return fmaxf(__uint_as_float(rr[0]), __uint_as_float(rr[1])); }
; DI float swapsum(float m) { auto rr = __builtin_amdgcn_permlane32_swap(__float_as_uint(m), __float_as_uint(m), false, false); return __uint_as_float(rr[0]) + __uint_as_float(rr[1]); }
; #define ATT_DECIDE(P0, P1, rm_) do { if (__any((rm_) > 6.0f)) { const float dl = fmaxf((rm_), 0.f); mhat += dl; const float f = EX(-dl); lsum *= f; \
;             _Pragma("unroll") for (int r = 0; r < 16; ++r) { P0[r] -= dl; P1[r] -= dl; negm[r] -= dl; } \
;             _Pragma("unroll") for (int i2 = 0; i2 < NDB; ++i2) _Pragma("unroll") for (int r = 0; r < 16; ++r) o[i2][r] *= f; } } while (0)
; template <int KIND> DI void attn_unit(const Params& P, int b, int h, int qb, char* shm, float lam, bool dry = false) {
;     ...
;         rm = swapmax(max3f(rm, rm2, rm2));
;         if (KIND == 2) {
;             const u32x2 kx = *(const LAS u32x2*)(shm3 + sc + 32768);
;             const float xk0 = __uint_as_float(kx.x << 16) + __uint_as_float(kx.x & 0xffff0000u) + __uint_as_float(kx.y << 16);
;             const float ltot = swapsum(lsum);
;             const bool ok = (qkmax + cb + xk0) < (mhat + __builtin_amdgcn_logf(ltot) - 54.0f);
;             const bool allok = __all(ok) && !(ATT_TILE(i) > wt_hi);
;             if (lane == 0) vote[8 * (i & 3) + wid] = allok ? 1u : 0u;
;         }
;         if (i + 1 < nt_eff) ATT_DECIDE(pb0, pb1, rm);
	v_max_f32_e32 v116, v116, v117
	v_cmp_lt_f32_e32 vcc, s3, v116
	s_cbranch_vccnz .Lhotc1_resc

; #define SBAR() __builtin_amdgcn_sched_barrier(0)
; #define PIN(x) asm volatile("" : "+v"(x))
; #define MF(a_, b_, c_) __builtin_amdgcn_mfma_f32_32x32x16_bf16(a_, b_, c_, 0, 0, 0)
; #define PVM(j_) o[(j_) % NDB] = MF(vq[(j_) & 3], pw[(j_) / NDB], o[(j_) % NDB])
; template <int KIND> DI void attn_unit(const Params& P, int b, int h, int qb, char* shm, float lam, bool dry = false) {
;     ...
;         ATT_KLD(sn, 0); ATT_XLD(sn);
;         SBAR();
;     ...
;         G1(pb0 = MF(kf[0], qr[0], negm), 0, w0, 0);  G1(pb1 = MF(kf[1], qr[0], negm), 2, w0, 1);
;         G1(pb0 = MF(kf[2], qr[1], pb0), 4, w0, 2);   G1(pb1 = MF(kf[3], qr[1], pb1), 6, w0, 3);
;         ATT_KLD(sn, 1);
;         SBAR();
;         G1(pb0 = MF(kf[0], qr[2], pb0), 8, w1, 0);   G1(pb1 = MF(kf[1], qr[2], pb1), 10, w1, 1);
;         LDV(0); SBAR();
;         G1(pb0 = MF(kf[2], qr[3], pb0), 12, w1, 2);
;         LDV(1); SBAR();
;         G1(pb1 = MF(kf[3], qr[3], pb1), 14, w1, 3);
;         LDV(2); SBAR();
;     ...
;         if (KIND == 2) { pb0 = MF(x0, ones, pb0); pb1 = MF(x1, ones, pb1); }
;         pw[0] = __builtin_bit_cast(bf16x8, w0); pw[1] = __builtin_bit_cast(bf16x8, w1);
;     ...
;         if (NDB == 4) {
;             LDV(3); PVM(0); E4(0, w0, 0); PIN(pa1); PIN(sacc); PIN(w0); SBAR();
;             LDV(4); PVM(1); E4(2, w0, 1); PIN(pa1); PIN(sacc); PIN(w0); SBAR();
;             LDV(5); PVM(2); E4(4, w0, 2); PIN(pa1); PIN(sacc); PIN(w0); SBAR();
;             LDV(6); PVM(3); E4(6, w0, 3); PIN(pa1); PIN(sacc); PIN(w0); SBAR();
;             LDV(7); PVM(4); E4(8, w1, 0); PIN(pa1); PIN(sacc); PIN(w1); SBAR();
;             LDV(8); PVM(5); E4(10, w1, 1); PIN(pa1); PIN(sacc); PIN(w1); SBAR();
;             LDV(9); PVM(6); E4(12, w1, 2); PIN(pa1); PIN(sacc); PIN(w1); SBAR();
;             LDV(10); PVM(7); E4(14, w1, 3); PIN(pa1); PIN(sacc); PIN(w1); SBAR();
;         } else {
;             LDV(3); PVM(0); E4(0, w0, 0); E4(2, w0, 1); PIN(pa1); PIN(sacc); PIN(w0); SBAR();
;             LDV(4); PVM(1); E4(4, w0, 2); E4(6, w0, 3); PIN(pa1); PIN(sacc); PIN(w0); SBAR();
;             LDV(5); PVM(2); E4(8, w1, 0); E4(10, w1, 1); PIN(pa1); PIN(sacc); PIN(w1); SBAR();
;             LDV(6); PVM(3); E4(12, w1, 2); E4(14, w1, 3); PIN(pa1); PIN(sacc); PIN(w1); SBAR();
;         }
;     ...
;         pw[2] = __builtin_bit_cast(bf16x8, w0); pw[3] = __builtin_bit_cast(bf16x8, w1);
;         lsum += sacc;
;         ATT_FIX(pb0, pb1, ATT_TILE(i + 1));
.Lct2_355:
	s_add_i32 s18, s34, 0x8400
	s_cmp_lg_u32 s34, 0x18c00
	s_cselect_b32 s29, s18, 0
	s_add_i32 s18, s29, 0
	v_add_u32_e32 v116, s18, v168
	v_add_u32_e32 v186, v116, v167
	ds_read_b128 v[4:7], v186
	ds_read_b128 v[174:177], v186 offset:512
	ds_read_b128 v[178:181], v186 offset:2048
	ds_read_b128 v[182:185], v186 offset:2560
	ds_read_b128 v[190:193], v116 offset:32768
	ds_read_b128 v[196:199], v116 offset:33280
	v_exp_f32_e32 v84, v84
	v_exp_f32_e32 v85, v85
	s_nop 0
	v_cvt_pk_bf16_f32 v152, v84, v85
	v_add_f32_e32 v116, 0, v84
	v_add_f32_e32 v116, v85, v116
	v_exp_f32_e32 v86, v86
	v_exp_f32_e32 v87, v87
	v_add_f32_e32 v116, v116, v86
	v_add_f32_e32 v116, v87, v116
	v_cvt_pk_bf16_f32 v153, v86, v87
	v_exp_f32_e32 v88, v88
	v_exp_f32_e32 v89, v89
	v_add_f32_e32 v116, v116, v88
	v_add_f32_e32 v187, v89, v116
	v_cvt_pk_bf16_f32 v154, v88, v89
	s_waitcnt lgkmcnt(5)
	v_mfma_f32_32x32x16_bf16 v[116:131], v[4:7], v[144:147], v[20:35]
	v_exp_f32_e32 v90, v90
	v_exp_f32_e32 v91, v91
	s_waitcnt lgkmcnt(4)
	v_mfma_f32_32x32x16_bf16 v[4:19], v[174:177], v[144:147], v[20:35]
	s_add_i32 s18, s34, 0
	v_exp_f32_e32 v92, v92
	v_exp_f32_e32 v93, v93
	s_waitcnt lgkmcnt(3)
	v_mfma_f32_32x32x16_bf16 v[116:131], v[178:181], v[140:143], v[116:131]
	v_add3_u32 v68, s18, v170, v171
	v_add_f32_e32 v72, v187, v90
	v_cvt_pk_bf16_f32 v148, v92, v93
	v_add_u32_e32 v164, v68, v172
	s_waitcnt lgkmcnt(0)
	v_add_f32_e32 v187, v91, v72
	v_cvt_pk_bf16_f32 v155, v90, v91
	v_mfma_f32_32x32x16_bf16 v[4:19], v[182:185], v[140:143], v[4:19]
	ds_read_b128 v[72:75], v186 offset:4096
	ds_read_b128 v[80:83], v186 offset:4608
	ds_read_b128 v[174:177], v186 offset:6144
	ds_read_b128 v[178:181], v186 offset:6656
	s_waitcnt lgkmcnt(3)
	v_mfma_f32_32x32x16_bf16 v[116:131], v[72:75], v[136:139], v[116:131]
	v_add_f32_e32 v72, v187, v92
	v_add_f32_e32 v72, v93, v72
	s_waitcnt lgkmcnt(2)
	v_mfma_f32_32x32x16_bf16 v[4:19], v[80:83], v[136:139], v[4:19]
	v_exp_f32_e32 v94, v94
	v_exp_f32_e32 v95, v95
	v_add_f32_e32 v72, v72, v94
	v_add_f32_e32 v80, v95, v72
	v_cvt_pk_bf16_f32 v149, v94, v95
	ds_read_b64_tr_b16 v[72:73], v164 offset:16384
	ds_read_b64_tr_b16 v[74:75], v164 offset:16896
	s_waitcnt lgkmcnt(3)
	v_mfma_f32_32x32x16_bf16 v[116:131], v[174:177], v[132:135], v[116:131]
	v_exp_f32_e32 v96, v96
	v_exp_f32_e32 v97, v97
	v_add_f32_e32 v80, v80, v96
	v_add_f32_e32 v174, v97, v80
	v_cvt_pk_bf16_f32 v150, v96, v97
	ds_read_b64_tr_b16 v[80:81], v164 offset:20480
	ds_read_b64_tr_b16 v[82:83], v164 offset:20992
	s_waitcnt lgkmcnt(4)
	v_mfma_f32_32x32x16_bf16 v[4:19], v[178:181], v[132:135], v[4:19]
	v_exp_f32_e32 v98, v98
	v_exp_f32_e32 v99, v99
	v_add_f32_e32 v151, v174, v98
	v_add_f32_e32 v174, v99, v151
	v_cvt_pk_bf16_f32 v151, v98, v99
	ds_read_b64_tr_b16 v[92:93], v164 offset:17408
	ds_read_b64_tr_b16 v[94:95], v164 offset:17920
	v_mfma_f32_32x32x16_bf16 v[116:131], v[190:193], v[0:3], v[116:131]
	v_exp_f32_e32 v100, v100
	v_exp_f32_e32 v101, v101
	v_exp_f32_e32 v102, v102
	v_exp_f32_e32 v103, v103
	v_cvt_pk_bf16_f32 v190, v100, v101
	v_mfma_f32_32x32x16_bf16 v[4:19], v[196:199], v[0:3], v[4:19]
	ds_read_b64_tr_b16 v[68:69], v164 offset:21504
	ds_read_b64_tr_b16 v[70:71], v164 offset:22016
	s_waitcnt lgkmcnt(6)
	v_mfma_f32_32x32x16_bf16 v[52:67], v[72:75], v[152:155], v[52:67]
	v_add_f32_e32 v72, v100, v174
	v_add_f32_e32 v76, v101, v72
	v_add_f32_e32 v73, v102, v76
	v_add_f32_e32 v76, v103, v73
	v_cvt_pk_bf16_f32 v191, v102, v103
	v_exp_f32_e32 v104, v104
	v_exp_f32_e32 v105, v105
	s_waitcnt lgkmcnt(4)
	v_mfma_f32_32x32x16_bf16 v[36:51], v[80:83], v[152:155], v[36:51]
	v_exp_f32_e32 v106, v106
	v_exp_f32_e32 v107, v107
	v_add_f32_e32 v74, v76, v104
	ds_read_b64_tr_b16 v[84:85], v164 offset:18432
	ds_read_b64_tr_b16 v[86:87], v164 offset:18944
	v_add_f32_e32 v75, v105, v74
	v_add_f32_e32 v75, v106, v75
	v_cvt_pk_bf16_f32 v192, v104, v105
	v_add_f32_e32 v76, v107, v75
	v_cvt_pk_bf16_f32 v193, v106, v107
	v_exp_f32_e32 v108, v108
	s_waitcnt lgkmcnt(4)
	v_mfma_f32_32x32x16_bf16 v[52:67], v[92:95], v[148:151], v[52:67]
	v_exp_f32_e32 v109, v109
	v_exp_f32_e32 v110, v110
	ds_read_b64_tr_b16 v[88:89], v164 offset:22528
	ds_read_b64_tr_b16 v[90:91], v164 offset:23040
	v_exp_f32_e32 v111, v111
	v_add_f32_e32 v72, v76, v108
	v_add_f32_e32 v76, v109, v72
	v_cvt_pk_bf16_f32 v152, v108, v109
	v_add_f32_e32 v73, v110, v76
	v_add_f32_e32 v76, v111, v73
	v_cvt_pk_bf16_f32 v153, v110, v111
	s_waitcnt lgkmcnt(4)
	v_mfma_f32_32x32x16_bf16 v[36:51], v[68:71], v[148:151], v[36:51]
	v_exp_f32_e32 v112, v112
	v_exp_f32_e32 v113, v113
	v_exp_f32_e32 v114, v114
	v_exp_f32_e32 v115, v115
	ds_read_b64_tr_b16 v[92:93], v164 offset:19456
	ds_read_b64_tr_b16 v[94:95], v164 offset:19968
	v_add_f32_e32 v68, v76, v112
	v_add_f32_e32 v68, v113, v68
	v_cvt_pk_bf16_f32 v154, v112, v113
	v_cvt_pk_bf16_f32 v155, v114, v115
	v_add_f32_e32 v68, v114, v68
	v_add_f32_e32 v68, v115, v68
	s_cmp_lg_u32 s22, s35
	s_cbranch_scc0 .Lhotc2_diag
.Lct2_357:
	s_add_i32 s19, s20, 2
	s_cmp_lt_i32 s19, 0
	s_cselect_b64 s[38:39], -1, 0
	s_cmp_gt_i32 s19, s36
	s_waitcnt lgkmcnt(4)
	v_mfma_f32_32x32x16_bf16 v[52:67], v[84:87], v[190:193], v[52:67]
	s_cselect_b64 vcc, -1, 0
	s_or_b64 vcc, s[38:39], vcc
	s_cbranch_vccnz .Lhotc2_mask

; #define LAS __attribute__((address_space(3)))
; DI float swapsum(float m) { auto rr = __builtin_amdgcn_permlane32_swap(__float_as_uint(m), __float_as_uint(m), false, false); return __uint_as_float(rr[0]) + __uint_as_float(rr[1]); }
; #define ATT_DECIDE(P0, P1, rm_) do { if (__any((rm_) > 6.0f)) { const float dl = fmaxf((rm_), 0.f); mhat += dl; const float f = EX(-dl); lsum *= f; \
;             _Pragma("unroll") for (int r = 0; r < 16; ++r) { P0[r] -= dl; P1[r] -= dl; negm[r] -= dl; } \
;             _Pragma("unroll") for (int i2 = 0; i2 < NDB; ++i2) _Pragma("unroll") for (int r = 0; r < 16; ++r) o[i2][r] *= f; } } while (0)
; template <int KIND> DI void attn_unit(const Params& P, int b, int h, int qb, char* shm, float lam, bool dry = false) {
;     ...
;         if (KIND == 2) {
;             const u32x2 kx = *(const LAS u32x2*)(shm3 + sc + 32768);
;             const float xk0 = __uint_as_float(kx.x << 16) + __uint_as_float(kx.x & 0xffff0000u) + __uint_as_float(kx.y << 16);
;             const float ltot = swapsum(lsum);
;             const bool ok = (qkmax + cb + xk0) < (mhat + __builtin_amdgcn_logf(ltot) - 54.0f);
;             const bool allok = __all(ok) && !(ATT_TILE(i) > wt_hi);
;             if (lane == 0) vote[8 * (i & 3) + wid] = allok ? 1u : 0u;
;         }
;         if (i + 1 < nt_eff) ATT_DECIDE(pb0, pb1, rm);
.Lct2_359:
	s_or_b64 exec, exec, s[38:39]
	v_cmp_ge_i32_e64 s[18:19], s31, v173
	s_and_b64 vcc, exec, s[18:19]
	s_cbranch_vccnz .Lct2_362


; #define LAS __attribute__((address_space(3)))
; DI float max3f(float a, float b, float c) { float r; asm("v_max3_f32 %0, %1, %2, %3" : "=v"(r) : "v"(a), "v"(b), "v"(c)); return r; }
; DI float swapmax(float m) { auto rr = __builtin_amdgcn_permlane32_swap(__float_as_uint(m), __float_as_uint(m), false, false); return fmaxf(__uint_as_float(rr[0]), __uint_as_float(rr[1])); }
; DI float swapsum(float m) { auto rr = __builtin_amdgcn_permlane32_swap(__float_as_uint(m), __float_as_uint(m), false, false); return __uint_as_float(rr[0]) + __uint_as_float(rr[1]); }
; #define ATT_DECIDE(P0, P1, rm_) do { if (__any((rm_) > 6.0f)) { const float dl = fmaxf((rm_), 0.f); mhat += dl; const float f = EX(-dl); lsum *= f; \
;             _Pragma("unroll") for (int r = 0; r < 16; ++r) { P0[r] -= dl; P1[r] -= dl; negm[r] -= dl; } \
;             _Pragma("unroll") for (int i2 = 0; i2 < NDB; ++i2) _Pragma("unroll") for (int r = 0; r < 16; ++r) o[i2][r] *= f; } } while (0)
; template <int KIND> DI void attn_unit(const Params& P, int b, int h, int qb, char* shm, float lam, bool dry = false) {
;     ...
;         rm = swapmax(max3f(rm, rm2, rm2));
;         if (KIND == 2) {
;             const u32x2 kx = *(const LAS u32x2*)(shm3 + sc + 32768);
;             const float xk0 = __uint_as_float(kx.x << 16) + __uint_as_float(kx.x & 0xffff0000u) + __uint_as_float(kx.y << 16);
;             const float ltot = swapsum(lsum);
;             const bool ok = (qkmax + cb + xk0) < (mhat + __builtin_amdgcn_logf(ltot) - 54.0f);
;             const bool allok = __all(ok) && !(ATT_TILE(i) > wt_hi);
;             if (lane == 0) vote[8 * (i & 3) + wid] = allok ? 1u : 0u;
;         }
;         if (i + 1 < nt_eff) ATT_DECIDE(pb0, pb1, rm);
	v_max_f32_e32 v84, v84, v85
	v_cmp_lt_f32_e32 vcc, s3, v84
	s_cbranch_vccnz .Lhotc2_resc

.Lhotc1_diag:
	v_cndmask_b32_e64 v4, v84, v245, s[48:49]
	v_cndmask_b32_e64 v100, v100, v245, s[50:51]
	v_cndmask_b32_e64 v85, v245, v85, s[52:53]
	v_cndmask_b32_e64 v84, v4, v84, s[52:53]
	v_cndmask_b32_e64 v101, v101, v245, s[54:55]
	v_cndmask_b32_e64 v86, v86, v245, s[56:57]
	v_cndmask_b32_e64 v102, v102, v245, s[58:59]
	v_cndmask_b32_e64 v87, v87, v245, s[60:61]
	v_cndmask_b32_e64 v103, v103, v245, s[62:63]
	v_cndmask_b32_e64 v88, v88, v245, s[64:65]
	v_cndmask_b32_e64 v104, v104, v245, s[66:67]
	v_cndmask_b32_e64 v89, v89, v245, s[68:69]
	v_cndmask_b32_e64 v105, v105, v245, s[70:71]
	v_cndmask_b32_e64 v90, v90, v245, s[72:73]
	v_cndmask_b32_e64 v106, v106, v245, s[74:75]
	v_cndmask_b32_e64 v91, v91, v245, s[76:77]
	v_cndmask_b32_e64 v107, v107, v245, s[78:79]
	v_cndmask_b32_e64 v92, v92, v245, s[80:81]
	v_cndmask_b32_e64 v108, v108, v245, s[82:83]
	v_cndmask_b32_e64 v93, v93, v245, s[84:85]
	v_cndmask_b32_e64 v109, v109, v245, s[86:87]
	v_cndmask_b32_e64 v94, v94, v245, s[88:89]
	v_cndmask_b32_e64 v110, v110, v245, s[90:91]
	v_cndmask_b32_e64 v95, v95, v245, s[92:93]
	v_cndmask_b32_e64 v111, v111, v245, s[94:95]
	v_cndmask_b32_e64 v96, v96, v245, s[96:97]
	v_cndmask_b32_e64 v112, v112, v245, s[4:5]
	v_cndmask_b32_e64 v97, v97, v245, s[6:7]
	v_cndmask_b32_e64 v113, v113, v245, s[8:9]
	v_cndmask_b32_e64 v98, v98, v245, s[10:11]
	v_cndmask_b32_e64 v114, v114, v245, s[12:13]
	v_cndmask_b32_e64 v99, v99, v245, s[14:15]
	v_cndmask_b32_e64 v115, v115, v245, s[16:17]
	s_branch .LBB0_357
.Lhotc2_diag:
	v_cndmask_b32_e64 v100, v116, v245, s[48:49]
	v_cndmask_b32_e64 v4, v4, v245, s[50:51]
	v_cndmask_b32_e64 v117, v245, v117, s[52:53]
	v_cndmask_b32_e64 v116, v100, v116, s[52:53]
	v_cndmask_b32_e64 v5, v5, v245, s[54:55]
	v_cndmask_b32_e64 v118, v118, v245, s[56:57]
	v_cndmask_b32_e64 v6, v6, v245, s[58:59]
	v_cndmask_b32_e64 v119, v119, v245, s[60:61]
	v_cndmask_b32_e64 v7, v7, v245, s[62:63]
	v_cndmask_b32_e64 v120, v120, v245, s[64:65]
	v_cndmask_b32_e64 v8, v8, v245, s[66:67]
	v_cndmask_b32_e64 v121, v121, v245, s[68:69]
	v_cndmask_b32_e64 v9, v9, v245, s[70:71]
	v_cndmask_b32_e64 v122, v122, v245, s[72:73]
	v_cndmask_b32_e64 v10, v10, v245, s[74:75]
	v_cndmask_b32_e64 v123, v123, v245, s[76:77]
	v_cndmask_b32_e64 v11, v11, v245, s[78:79]
	v_cndmask_b32_e64 v124, v124, v245, s[80:81]
	v_cndmask_b32_e64 v12, v12, v245, s[82:83]
	v_cndmask_b32_e64 v125, v125, v245, s[84:85]
	v_cndmask_b32_e64 v13, v13, v245, s[86:87]
	v_cndmask_b32_e64 v126, v126, v245, s[88:89]
	v_cndmask_b32_e64 v14, v14, v245, s[90:91]
	v_cndmask_b32_e64 v127, v127, v245, s[92:93]
	v_cndmask_b32_e64 v15, v15, v245, s[94:95]
	v_cndmask_b32_e64 v128, v128, v245, s[96:97]
	v_cndmask_b32_e64 v16, v16, v245, s[4:5]
	v_cndmask_b32_e64 v129, v129, v245, s[6:7]
	v_cndmask_b32_e64 v17, v17, v245, s[8:9]
	v_cndmask_b32_e64 v130, v130, v245, s[10:11]
	v_cndmask_b32_e64 v18, v18, v245, s[12:13]
	v_cndmask_b32_e64 v131, v131, v245, s[14:15]
	v_cndmask_b32_e64 v19, v19, v245, s[16:17]
	s_branch .Lct2_357
.Lhotc1_mask:
	v_mov_b32_e32 v84, v245
	v_mov_b32_e32 v85, v245
	v_mov_b32_e32 v86, v245
	v_mov_b32_e32 v87, v245
	v_mov_b32_e32 v88, v245
	v_mov_b32_e32 v89, v245
	v_mov_b32_e32 v90, v245
	v_mov_b32_e32 v91, v245
	v_mov_b32_e32 v92, v245
	v_mov_b32_e32 v93, v245
	v_mov_b32_e32 v94, v245
	v_mov_b32_e32 v95, v245
	v_mov_b32_e32 v96, v245
	v_mov_b32_e32 v97, v245
	v_mov_b32_e32 v98, v245
	v_mov_b32_e32 v99, v245
	v_mov_b32_e32 v100, v245
	v_mov_b32_e32 v101, v245
	v_mov_b32_e32 v102, v245
	v_mov_b32_e32 v103, v245
	v_mov_b32_e32 v104, v245
	v_mov_b32_e32 v105, v245
	v_mov_b32_e32 v106, v245
	v_mov_b32_e32 v107, v245
	v_mov_b32_e32 v108, v245
	v_mov_b32_e32 v109, v245
	v_mov_b32_e32 v110, v245
	v_mov_b32_e32 v111, v245
	v_mov_b32_e32 v112, v245
	v_mov_b32_e32 v113, v245
	v_mov_b32_e32 v114, v245
	v_mov_b32_e32 v115, v245
	s_branch .Lct1_nomask
.Lhotc2_mask:
	v_mov_b32_e32 v116, v245
	v_mov_b32_e32 v117, v245
	v_mov_b32_e32 v118, v245
	v_mov_b32_e32 v119, v245
	v_mov_b32_e32 v120, v245
	v_mov_b32_e32 v121, v245
	v_mov_b32_e32 v122, v245
	v_mov_b32_e32 v123, v245
	v_mov_b32_e32 v124, v245
	v_mov_b32_e32 v125, v245
	v_mov_b32_e32 v126, v245
	v_mov_b32_e32 v127, v245
	v_mov_b32_e32 v128, v245
	v_mov_b32_e32 v129, v245
	v_mov_b32_e32 v130, v245
	v_mov_b32_e32 v131, v245
	v_mov_b32_e32 v4, v245
	v_mov_b32_e32 v5, v245
	v_mov_b32_e32 v6, v245
	v_mov_b32_e32 v7, v245
	v_mov_b32_e32 v8, v245
	v_mov_b32_e32 v9, v245
	v_mov_b32_e32 v10, v245
	v_mov_b32_e32 v11, v245
	v_mov_b32_e32 v12, v245
	v_mov_b32_e32 v13, v245
	v_mov_b32_e32 v14, v245
	v_mov_b32_e32 v15, v245
	v_mov_b32_e32 v16, v245
	v_mov_b32_e32 v17, v245
	v_mov_b32_e32 v18, v245
	v_mov_b32_e32 v19, v245
	s_branch .Lct2x_nomask
.Lhotc1_resc:
	v_max_f32_e32 v116, v116, v116
	v_max_f32_e32 v117, 0, v116
	v_exp_f32_e64 v116, -v117
	v_add_f32_e32 v165, v165, v117
	v_sub_f32_e32 v99, v99, v117
	v_sub_f32_e32 v98, v98, v117
	v_pk_mul_f32 v[50:51], v[50:51], v[116:117] op_sel_hi:[1,0]
	v_pk_mul_f32 v[48:49], v[48:49], v[116:117] op_sel_hi:[1,0]
	v_pk_mul_f32 v[46:47], v[46:47], v[116:117] op_sel_hi:[1,0]
	v_pk_mul_f32 v[44:45], v[44:45], v[116:117] op_sel_hi:[1,0]
	v_pk_mul_f32 v[42:43], v[42:43], v[116:117] op_sel_hi:[1,0]
	v_pk_mul_f32 v[40:41], v[40:41], v[116:117] op_sel_hi:[1,0]
	v_pk_mul_f32 v[38:39], v[38:39], v[116:117] op_sel_hi:[1,0]
	v_pk_mul_f32 v[36:37], v[36:37], v[116:117] op_sel_hi:[1,0]
	v_pk_mul_f32 v[66:67], v[66:67], v[116:117] op_sel_hi:[1,0]
	v_pk_mul_f32 v[64:65], v[64:65], v[116:117] op_sel_hi:[1,0]
	v_pk_mul_f32 v[62:63], v[62:63], v[116:117] op_sel_hi:[1,0]
	v_pk_mul_f32 v[60:61], v[60:61], v[116:117] op_sel_hi:[1,0]
	v_pk_mul_f32 v[58:59], v[58:59], v[116:117] op_sel_hi:[1,0]
	v_pk_mul_f32 v[56:57], v[56:57], v[116:117] op_sel_hi:[1,0]
	v_pk_mul_f32 v[54:55], v[54:55], v[116:117] op_sel_hi:[1,0]
	v_pk_mul_f32 v[52:53], v[52:53], v[116:117] op_sel_hi:[1,0]
	v_sub_f32_e32 v97, v97, v117
	v_sub_f32_e32 v96, v96, v117
	v_sub_f32_e32 v95, v95, v117
	v_sub_f32_e32 v94, v94, v117
	v_sub_f32_e32 v93, v93, v117
	v_sub_f32_e32 v92, v92, v117
	v_sub_f32_e32 v91, v91, v117
	v_sub_f32_e32 v90, v90, v117
	v_sub_f32_e32 v89, v89, v117
	v_sub_f32_e32 v88, v88, v117
	v_sub_f32_e32 v87, v87, v117
	v_sub_f32_e32 v86, v86, v117
	v_sub_f32_e32 v85, v85, v117
	v_sub_f32_e32 v84, v84, v117
	v_sub_f32_e32 v115, v115, v117
	v_sub_f32_e32 v114, v114, v117
	v_sub_f32_e32 v113, v113, v117
	v_sub_f32_e32 v112, v112, v117
	v_sub_f32_e32 v111, v111, v117
	v_sub_f32_e32 v110, v110, v117
	v_sub_f32_e32 v109, v109, v117
	v_sub_f32_e32 v108, v108, v117
	v_sub_f32_e32 v107, v107, v117
	v_sub_f32_e32 v106, v106, v117
	v_sub_f32_e32 v105, v105, v117
	v_sub_f32_e32 v104, v104, v117
	v_sub_f32_e32 v103, v103, v117
	v_sub_f32_e32 v102, v102, v117
	v_sub_f32_e32 v101, v101, v117
	v_sub_f32_e32 v100, v100, v117
	v_sub_f32_e32 v35, v35, v117
	v_sub_f32_e32 v34, v34, v117
	v_sub_f32_e32 v33, v33, v117
	v_sub_f32_e32 v32, v32, v117
	v_sub_f32_e32 v31, v31, v117
	v_sub_f32_e32 v30, v30, v117
	v_sub_f32_e32 v29, v29, v117
	v_sub_f32_e32 v28, v28, v117
	v_sub_f32_e32 v27, v27, v117
	v_sub_f32_e32 v26, v26, v117
	v_sub_f32_e32 v25, v25, v117
	v_sub_f32_e32 v24, v24, v117
	v_sub_f32_e32 v23, v23, v117
	v_sub_f32_e32 v22, v22, v117
	v_sub_f32_e32 v21, v21, v117
	v_sub_f32_e32 v20, v20, v117
	v_mul_f32_e32 v169, v169, v116
	s_branch .LBB0_362
.Lhotc2_resc:
	v_max_f32_e32 v84, v84, v84
	v_max_f32_e32 v85, 0, v84
	v_exp_f32_e64 v84, -v85
	v_add_f32_e32 v165, v165, v85
	v_sub_f32_e32 v131, v131, v85
	v_sub_f32_e32 v130, v130, v85
	v_pk_mul_f32 v[50:51], v[50:51], v[84:85] op_sel_hi:[1,0]
	v_pk_mul_f32 v[48:49], v[48:49], v[84:85] op_sel_hi:[1,0]
	v_pk_mul_f32 v[46:47], v[46:47], v[84:85] op_sel_hi:[1,0]
	v_pk_mul_f32 v[44:45], v[44:45], v[84:85] op_sel_hi:[1,0]
	v_pk_mul_f32 v[42:43], v[42:43], v[84:85] op_sel_hi:[1,0]
	v_pk_mul_f32 v[40:41], v[40:41], v[84:85] op_sel_hi:[1,0]
	v_pk_mul_f32 v[38:39], v[38:39], v[84:85] op_sel_hi:[1,0]
	v_pk_mul_f32 v[36:37], v[36:37], v[84:85] op_sel_hi:[1,0]
	v_pk_mul_f32 v[66:67], v[66:67], v[84:85] op_sel_hi:[1,0]
	v_pk_mul_f32 v[64:65], v[64:65], v[84:85] op_sel_hi:[1,0]
	v_pk_mul_f32 v[62:63], v[62:63], v[84:85] op_sel_hi:[1,0]
	v_pk_mul_f32 v[60:61], v[60:61], v[84:85] op_sel_hi:[1,0]
	v_pk_mul_f32 v[58:59], v[58:59], v[84:85] op_sel_hi:[1,0]
	v_pk_mul_f32 v[56:57], v[56:57], v[84:85] op_sel_hi:[1,0]
	v_pk_mul_f32 v[54:55], v[54:55], v[84:85] op_sel_hi:[1,0]
	v_pk_mul_f32 v[52:53], v[52:53], v[84:85] op_sel_hi:[1,0]
	v_sub_f32_e32 v129, v129, v85
	v_sub_f32_e32 v128, v128, v85
	v_sub_f32_e32 v127, v127, v85
	v_sub_f32_e32 v126, v126, v85
	v_sub_f32_e32 v125, v125, v85
	v_sub_f32_e32 v124, v124, v85
	v_sub_f32_e32 v123, v123, v85
	v_sub_f32_e32 v122, v122, v85
	v_sub_f32_e32 v121, v121, v85
	v_sub_f32_e32 v120, v120, v85
	v_sub_f32_e32 v119, v119, v85
	v_sub_f32_e32 v118, v118, v85
	v_sub_f32_e32 v117, v117, v85
	v_sub_f32_e32 v116, v116, v85
	v_sub_f32_e32 v19, v19, v85
	v_sub_f32_e32 v18, v18, v85
	v_sub_f32_e32 v17, v17, v85
	v_sub_f32_e32 v16, v16, v85
	v_sub_f32_e32 v15, v15, v85
	v_sub_f32_e32 v14, v14, v85
	v_sub_f32_e32 v13, v13, v85
	v_sub_f32_e32 v12, v12, v85
	v_sub_f32_e32 v11, v11, v85
	v_sub_f32_e32 v10, v10, v85
	v_sub_f32_e32 v9, v9, v85
	v_sub_f32_e32 v8, v8, v85
	v_sub_f32_e32 v7, v7, v85
	v_sub_f32_e32 v6, v6, v85
	v_sub_f32_e32 v5, v5, v85
	v_sub_f32_e32 v4, v4, v85
	v_sub_f32_e32 v35, v35, v85
	v_sub_f32_e32 v34, v34, v85
	v_sub_f32_e32 v33, v33, v85
	v_sub_f32_e32 v32, v32, v85
	v_sub_f32_e32 v31, v31, v85
	v_sub_f32_e32 v30, v30, v85
	v_sub_f32_e32 v29, v29, v85
	v_sub_f32_e32 v28, v28, v85
	v_sub_f32_e32 v27, v27, v85
	v_sub_f32_e32 v26, v26, v85
	v_sub_f32_e32 v25, v25, v85
	v_sub_f32_e32 v24, v24, v85
	v_sub_f32_e32 v23, v23, v85
	v_sub_f32_e32 v22, v22, v85
	v_sub_f32_e32 v21, v21, v85
	v_sub_f32_e32 v20, v20, v85
	v_mul_f32_e32 v169, v169, v84
	s_branch .Lct2_362
